# NSA lazy rescale: per-lane trigger, cross-half max exchange (bpermute) only on the rescale path
# speedup vs baseline: 1.0166x; 1.0068x over previous
.LBB0_283:
	s_add_i32 s13, s12, 1
	s_min_i32 s4, s13, s10
	s_lshl_b32 s96, s4, 6
	s_lshl_b64 s[6:7], s[96:97], 7
	s_lshl_b64 s[4:5], s[96:97], 1
	v_lshl_add_u64 v[2:3], v[190:191], 0, s[6:7]
	global_load_dwordx4 v[8:11], v[2:3], off offset:-2048
	s_nop 0
	global_load_dwordx4 v[4:7], v[2:3], off offset:2048
	v_lshl_add_u64 v[2:3], v[162:163], 0, s[4:5]
	v_lshl_add_u64 v[48:49], v[164:165], 0, s[4:5]
	global_load_dwordx4 v[12:15], v[2:3], off
	global_load_dwordx4 v[112:115], v[48:49], off
	s_and_b32 s14, s12, 1
	s_mul_i32 s4, s14, 0x4800
	v_lshrrev_b64 v[2:3], s12, v[128:129]
	s_lshl_b32 s15, s12, 6
	v_and_b32_e32 v0, 1, v2
	s_or_b32 s5, s15, 63
	v_or_b32_e32 v3, s4, v131
	v_cmp_eq_u64_e64 s[38:39], 0, v[0:1]
	s_cmp_gt_i32 s5, s8
	v_add_u32_e32 v172, v3, v161
	s_mov_b64 s[4:5], -1
	s_cbranch_scc1 .LBB0_289
	v_mad_u32_u24 v0, v217, s37, v3
	v_lshl_add_u32 v215, v156, 1, v3
	ds_read_b128 v[220:223], v0
	ds_read_b128 v[236:239], v0 offset:4608
	ds_read_b128 v[224:227], v0 offset:32
	ds_read_b128 v[240:243], v0 offset:4640
	ds_read_b128 v[228:231], v0 offset:64
	ds_read_b128 v[244:247], v0 offset:4672
	ds_read_b128 v[232:235], v0 offset:96
	ds_read_b128 v[248:251], v0 offset:4704
	ds_read_b128 v[64:67], v215 offset:9216
	ds_read_b128 v[68:71], v215 offset:13824
	ds_read_b128 v[72:75], v215 offset:9248
	ds_read_b128 v[76:79], v215 offset:13856
	s_waitcnt lgkmcnt(11)
	v_mfma_f32_32x32x16_bf16 v[80:95], v[220:223], v[96:99], 0
	s_waitcnt lgkmcnt(10)
	v_mfma_f32_32x32x16_bf16 v[48:63], v[236:239], v[96:99], 0
	s_waitcnt lgkmcnt(9)
	v_mfma_f32_32x32x16_bf16 v[80:95], v[224:227], v[100:103], v[80:95]
	s_waitcnt lgkmcnt(8)
	v_mfma_f32_32x32x16_bf16 v[48:63], v[240:243], v[100:103], v[48:63]
	s_waitcnt lgkmcnt(7)
	v_mfma_f32_32x32x16_bf16 v[80:95], v[228:231], v[104:107], v[80:95]
	s_waitcnt lgkmcnt(6)
	v_mfma_f32_32x32x16_bf16 v[48:63], v[244:247], v[104:107], v[48:63]
	s_waitcnt lgkmcnt(5)
	v_mfma_f32_32x32x16_bf16 v[80:95], v[232:235], v[108:111], v[80:95]
	s_waitcnt lgkmcnt(4)
	v_mfma_f32_32x32x16_bf16 v[48:63], v[248:251], v[108:111], v[48:63]
	ds_read_b128 v[220:223], v215 offset:9280
	ds_read_b128 v[224:227], v215 offset:13888
	ds_read_b128 v[228:231], v215 offset:9312
	ds_read_b128 v[232:235], v215 offset:13920
	s_nop 7
	v_max3_f32 v0, v80, v81, v82
	v_max3_f32 v2, v88, v89, v90
	v_max3_f32 v0, v0, v83, v84
	v_max3_f32 v2, v2, v91, v92
	v_max3_f32 v0, v0, v85, v86
	v_max3_f32 v2, v2, v93, v94
	v_max3_f32 v0, v0, v87, v95
	v_max_f32_e32 v0, v0, v2
	v_max3_f32 v175, v48, v49, v50
	v_max3_f32 v214, v56, v57, v58
	v_max3_f32 v175, v175, v51, v52
	v_max3_f32 v214, v214, v59, v60
	v_max3_f32 v175, v175, v53, v54
	v_max3_f32 v214, v214, v61, v62
	v_max3_f32 v175, v175, v55, v63
	v_max_f32_e32 v175, v175, v214
	v_cmp_gt_f32_e32 vcc, v0, v219
	s_andn2_b64 vcc, vcc, s[38:39]
	s_cmp_eq_u64 vcc, 0
	s_cbranch_scc1 .Lnsw_keep0
	v_cndmask_b32_e64 v0, v0, v202, s[38:39]
	s_nop 0
	ds_bpermute_b32 v2, v119, v0
	s_waitcnt lgkmcnt(0)
	v_max_f32_e32 v0, v0, v2
	v_max_f32_e32 v173, v167, v0
	v_sub_f32_e32 v0, v167, v173
	v_exp_f32_e32 v0, v0
	v_mov_b32_e32 v167, v173
	v_add_f32_e32 v219, 0x41200000, v173
	v_mul_f32_e32 v169, v169, v0
	v_pk_mul_f32 v[46:47], v[46:47], v[0:1] op_sel_hi:[1,0]
	v_pk_mul_f32 v[44:45], v[44:45], v[0:1] op_sel_hi:[1,0]
	v_pk_mul_f32 v[42:43], v[42:43], v[0:1] op_sel_hi:[1,0]
	v_pk_mul_f32 v[40:41], v[40:41], v[0:1] op_sel_hi:[1,0]
	v_pk_mul_f32 v[38:39], v[38:39], v[0:1] op_sel_hi:[1,0]
	v_pk_mul_f32 v[36:37], v[36:37], v[0:1] op_sel_hi:[1,0]
	v_pk_mul_f32 v[34:35], v[34:35], v[0:1] op_sel_hi:[1,0]
	v_pk_mul_f32 v[32:33], v[32:33], v[0:1] op_sel_hi:[1,0]
	v_pk_mul_f32 v[30:31], v[30:31], v[0:1] op_sel_hi:[1,0]
	v_pk_mul_f32 v[28:29], v[28:29], v[0:1] op_sel_hi:[1,0]
	v_pk_mul_f32 v[26:27], v[26:27], v[0:1] op_sel_hi:[1,0]
	v_pk_mul_f32 v[24:25], v[24:25], v[0:1] op_sel_hi:[1,0]
	v_pk_mul_f32 v[22:23], v[22:23], v[0:1] op_sel_hi:[1,0]
	v_pk_mul_f32 v[20:21], v[20:21], v[0:1] op_sel_hi:[1,0]
	v_pk_mul_f32 v[18:19], v[18:19], v[0:1] op_sel_hi:[1,0]
	v_pk_mul_f32 v[16:17], v[16:17], v[0:1] op_sel_hi:[1,0]
.Lnsw_keep0:
	v_cndmask_b32_e64 v174, v167, v206, s[38:39]
	v_sub_f32_e32 v80, v80, v174
	v_exp_f32_e32 v80, v80
	v_sub_f32_e32 v81, v81, v174
	v_exp_f32_e32 v81, v81
	v_sub_f32_e32 v82, v82, v174
	v_exp_f32_e32 v82, v82
	v_add_f32_e32 v213, v81, v80
	v_sub_f32_e32 v83, v83, v174
	v_exp_f32_e32 v83, v83
	v_add_f32_e32 v213, v82, v213
	v_cvt_pk_bf16_f32 v176, v80, v81
	v_sub_f32_e32 v84, v84, v174
	v_exp_f32_e32 v84, v84
	v_add_f32_e32 v213, v83, v213
	v_sub_f32_e32 v85, v85, v174
	v_exp_f32_e32 v85, v85
	v_add_f32_e32 v213, v84, v213
	v_cvt_pk_bf16_f32 v177, v82, v83
	v_sub_f32_e32 v86, v86, v174
	v_exp_f32_e32 v86, v86
	v_add_f32_e32 v213, v85, v213
	v_sub_f32_e32 v87, v87, v174
	v_exp_f32_e32 v87, v87
	v_add_f32_e32 v213, v86, v213
	v_cvt_pk_bf16_f32 v178, v84, v85
	v_sub_f32_e32 v88, v88, v174
	v_exp_f32_e32 v88, v88
	v_add_f32_e32 v213, v87, v213
	v_sub_f32_e32 v89, v89, v174
	v_exp_f32_e32 v89, v89
	v_add_f32_e32 v213, v88, v213
	v_cvt_pk_bf16_f32 v179, v86, v87
	v_sub_f32_e32 v90, v90, v174
	v_exp_f32_e32 v90, v90
	v_add_f32_e32 v213, v89, v213
	s_waitcnt lgkmcnt(7)
	v_mfma_f32_32x32x16_bf16 v[32:47], v[64:67], v[176:179], v[32:47]
	s_waitcnt lgkmcnt(6)
	v_mfma_f32_32x32x16_bf16 v[16:31], v[68:71], v[176:179], v[16:31]
	v_sub_f32_e32 v91, v91, v174
	v_exp_f32_e32 v91, v91
	v_add_f32_e32 v213, v90, v213
	v_cvt_pk_bf16_f32 v180, v88, v89
	v_sub_f32_e32 v92, v92, v174
	v_exp_f32_e32 v92, v92
	v_add_f32_e32 v213, v91, v213
	v_sub_f32_e32 v93, v93, v174
	v_exp_f32_e32 v93, v93
	v_add_f32_e32 v213, v92, v213
	v_cvt_pk_bf16_f32 v181, v90, v91
	v_sub_f32_e32 v94, v94, v174
	v_exp_f32_e32 v94, v94
	v_add_f32_e32 v213, v93, v213
	v_sub_f32_e32 v95, v95, v174
	v_exp_f32_e32 v95, v95
	v_add_f32_e32 v213, v94, v213
	v_cvt_pk_bf16_f32 v182, v92, v93
	v_add_f32_e32 v213, v95, v213
	v_cvt_pk_bf16_f32 v183, v94, v95
	v_add_f32_e32 v169, v169, v213
	s_nop 0
	s_waitcnt lgkmcnt(5)
	v_mfma_f32_32x32x16_bf16 v[32:47], v[72:75], v[180:183], v[32:47]
	s_waitcnt lgkmcnt(4)
	v_mfma_f32_32x32x16_bf16 v[16:31], v[76:79], v[180:183], v[16:31]
	v_cmp_gt_f32_e32 vcc, v175, v219
	s_andn2_b64 vcc, vcc, s[38:39]
	s_cmp_eq_u64 vcc, 0
	s_cbranch_scc1 .Lnsw_keep1
	v_cndmask_b32_e64 v175, v175, v202, s[38:39]
	s_nop 0
	ds_bpermute_b32 v214, v119, v175
	s_waitcnt lgkmcnt(0)
	v_max_f32_e32 v175, v175, v214
	v_max_f32_e32 v173, v167, v175
	v_sub_f32_e32 v0, v167, v173
	v_exp_f32_e32 v0, v0
	v_mov_b32_e32 v167, v173
	v_add_f32_e32 v219, 0x41200000, v173
	v_mul_f32_e32 v169, v169, v0
	v_pk_mul_f32 v[46:47], v[46:47], v[0:1] op_sel_hi:[1,0]
	v_pk_mul_f32 v[44:45], v[44:45], v[0:1] op_sel_hi:[1,0]
	v_pk_mul_f32 v[42:43], v[42:43], v[0:1] op_sel_hi:[1,0]
	v_pk_mul_f32 v[40:41], v[40:41], v[0:1] op_sel_hi:[1,0]
	v_pk_mul_f32 v[38:39], v[38:39], v[0:1] op_sel_hi:[1,0]
	v_pk_mul_f32 v[36:37], v[36:37], v[0:1] op_sel_hi:[1,0]
	v_pk_mul_f32 v[34:35], v[34:35], v[0:1] op_sel_hi:[1,0]
	v_pk_mul_f32 v[32:33], v[32:33], v[0:1] op_sel_hi:[1,0]
	v_pk_mul_f32 v[30:31], v[30:31], v[0:1] op_sel_hi:[1,0]
	v_pk_mul_f32 v[28:29], v[28:29], v[0:1] op_sel_hi:[1,0]
	v_pk_mul_f32 v[26:27], v[26:27], v[0:1] op_sel_hi:[1,0]
	v_pk_mul_f32 v[24:25], v[24:25], v[0:1] op_sel_hi:[1,0]
	v_pk_mul_f32 v[22:23], v[22:23], v[0:1] op_sel_hi:[1,0]
	v_pk_mul_f32 v[20:21], v[20:21], v[0:1] op_sel_hi:[1,0]
	v_pk_mul_f32 v[18:19], v[18:19], v[0:1] op_sel_hi:[1,0]
	v_pk_mul_f32 v[16:17], v[16:17], v[0:1] op_sel_hi:[1,0]
.Lnsw_keep1:
	v_cndmask_b32_e64 v174, v167, v206, s[38:39]
	v_sub_f32_e32 v48, v48, v174
	v_exp_f32_e32 v48, v48
	v_sub_f32_e32 v49, v49, v174
	v_exp_f32_e32 v49, v49
	v_sub_f32_e32 v50, v50, v174
	v_exp_f32_e32 v50, v50
	v_add_f32_e32 v213, v49, v48
	v_sub_f32_e32 v51, v51, v174
	v_exp_f32_e32 v51, v51
	v_add_f32_e32 v213, v50, v213
	v_cvt_pk_bf16_f32 v80, v48, v49
	v_sub_f32_e32 v52, v52, v174
	v_exp_f32_e32 v52, v52
	v_add_f32_e32 v213, v51, v213
	v_sub_f32_e32 v53, v53, v174
	v_exp_f32_e32 v53, v53
	v_add_f32_e32 v213, v52, v213
	v_cvt_pk_bf16_f32 v81, v50, v51
	v_sub_f32_e32 v54, v54, v174
	v_exp_f32_e32 v54, v54
	v_add_f32_e32 v213, v53, v213
	v_sub_f32_e32 v55, v55, v174
	v_exp_f32_e32 v55, v55
	v_add_f32_e32 v213, v54, v213
	v_cvt_pk_bf16_f32 v82, v52, v53
	v_sub_f32_e32 v56, v56, v174
	v_exp_f32_e32 v56, v56
	v_add_f32_e32 v213, v55, v213
	v_sub_f32_e32 v57, v57, v174
	v_exp_f32_e32 v57, v57
	v_add_f32_e32 v213, v56, v213
	v_cvt_pk_bf16_f32 v83, v54, v55
	v_sub_f32_e32 v58, v58, v174
	v_exp_f32_e32 v58, v58
	v_add_f32_e32 v213, v57, v213
	s_waitcnt lgkmcnt(3)
	v_mfma_f32_32x32x16_bf16 v[32:47], v[220:223], v[80:83], v[32:47]
	s_waitcnt lgkmcnt(2)
	v_mfma_f32_32x32x16_bf16 v[16:31], v[224:227], v[80:83], v[16:31]
	v_sub_f32_e32 v59, v59, v174
	v_exp_f32_e32 v59, v59
	v_add_f32_e32 v213, v58, v213
	v_cvt_pk_bf16_f32 v84, v56, v57
	v_sub_f32_e32 v60, v60, v174
	v_exp_f32_e32 v60, v60
	v_add_f32_e32 v213, v59, v213
	v_sub_f32_e32 v61, v61, v174
	v_exp_f32_e32 v61, v61
	v_add_f32_e32 v213, v60, v213
	v_cvt_pk_bf16_f32 v85, v58, v59
	v_sub_f32_e32 v62, v62, v174
	v_exp_f32_e32 v62, v62
	v_add_f32_e32 v213, v61, v213
	v_sub_f32_e32 v63, v63, v174
	v_exp_f32_e32 v63, v63
	v_add_f32_e32 v213, v62, v213
	v_cvt_pk_bf16_f32 v86, v60, v61
	v_add_f32_e32 v213, v63, v213
	v_cvt_pk_bf16_f32 v87, v62, v63
	v_add_f32_e32 v169, v169, v213
	s_nop 0
	s_waitcnt lgkmcnt(1)
	v_mfma_f32_32x32x16_bf16 v[32:47], v[228:231], v[84:87], v[32:47]
	s_waitcnt lgkmcnt(0)
	v_mfma_f32_32x32x16_bf16 v[16:31], v[232:235], v[84:87], v[16:31]
	s_branch .LBB0_296

.LBB0_307:
	s_and_b64 vcc, exec, s[4:5]
	s_cbranch_vccz .Lnsw1_edgeback
	v_mad_u32_u24 v0, v218, s37, v14
	v_lshl_add_u32 v215, v159, 1, v14
	ds_read_b128 v[220:223], v0
	ds_read_b128 v[236:239], v0 offset:4608
	ds_read_b128 v[224:227], v0 offset:32
	ds_read_b128 v[240:243], v0 offset:4640
	ds_read_b128 v[228:231], v0 offset:64
	ds_read_b128 v[244:247], v0 offset:4672
	ds_read_b128 v[232:235], v0 offset:96
	ds_read_b128 v[248:251], v0 offset:4704
	ds_read_b128 v[64:67], v215 offset:9216
	ds_read_b128 v[68:71], v215 offset:13824
	ds_read_b128 v[72:75], v215 offset:9248
	ds_read_b128 v[76:79], v215 offset:13856
	s_waitcnt lgkmcnt(11)
	v_mfma_f32_32x32x16_bf16 v[80:95], v[220:223], v[96:99], 0
	s_waitcnt lgkmcnt(10)
	v_mfma_f32_32x32x16_bf16 v[48:63], v[236:239], v[96:99], 0
	s_waitcnt lgkmcnt(9)
	v_mfma_f32_32x32x16_bf16 v[80:95], v[224:227], v[100:103], v[80:95]
	s_waitcnt lgkmcnt(8)
	v_mfma_f32_32x32x16_bf16 v[48:63], v[240:243], v[100:103], v[48:63]
	s_waitcnt lgkmcnt(7)
	v_mfma_f32_32x32x16_bf16 v[80:95], v[228:231], v[104:107], v[80:95]
	s_waitcnt lgkmcnt(6)
	v_mfma_f32_32x32x16_bf16 v[48:63], v[244:247], v[104:107], v[48:63]
	s_waitcnt lgkmcnt(5)
	v_mfma_f32_32x32x16_bf16 v[80:95], v[232:235], v[108:111], v[80:95]
	s_waitcnt lgkmcnt(4)
	v_mfma_f32_32x32x16_bf16 v[48:63], v[248:251], v[108:111], v[48:63]
	ds_read_b128 v[220:223], v215 offset:9280
	ds_read_b128 v[224:227], v215 offset:13888
	ds_read_b128 v[228:231], v215 offset:9312
	ds_read_b128 v[232:235], v215 offset:13920
	s_nop 7
	v_max3_f32 v0, v80, v81, v82
	v_max3_f32 v216, v88, v89, v90
	v_max3_f32 v0, v0, v83, v84
	v_max3_f32 v216, v216, v91, v92
	v_max3_f32 v0, v0, v85, v86
	v_max3_f32 v216, v216, v93, v94
	v_max3_f32 v0, v0, v87, v95
	v_max_f32_e32 v0, v0, v216
	v_max3_f32 v175, v48, v49, v50
	v_max3_f32 v214, v56, v57, v58
	v_max3_f32 v175, v175, v51, v52
	v_max3_f32 v214, v214, v59, v60
	v_max3_f32 v175, v175, v53, v54
	v_max3_f32 v214, v214, v61, v62
	v_max3_f32 v175, v175, v55, v63
	v_max_f32_e32 v175, v175, v214
	v_cmp_gt_f32_e32 vcc, v0, v219
	s_cmp_eq_u64 vcc, 0
	s_cbranch_scc1 .Lnsw1_keep0
	s_nop 0
	ds_bpermute_b32 v216, v119, v0
	s_waitcnt lgkmcnt(0)
	v_max_f32_e32 v0, v0, v216
	v_max_f32_e32 v173, v168, v0
	v_sub_f32_e32 v0, v168, v173
	v_exp_f32_e32 v0, v0
	v_mov_b32_e32 v168, v173
	v_add_f32_e32 v219, 0x41200000, v173
	v_mul_f32_e32 v169, v169, v0
	v_pk_mul_f32 v[46:47], v[46:47], v[0:1] op_sel_hi:[1,0]
	v_pk_mul_f32 v[44:45], v[44:45], v[0:1] op_sel_hi:[1,0]
	v_pk_mul_f32 v[42:43], v[42:43], v[0:1] op_sel_hi:[1,0]
	v_pk_mul_f32 v[40:41], v[40:41], v[0:1] op_sel_hi:[1,0]
	v_pk_mul_f32 v[38:39], v[38:39], v[0:1] op_sel_hi:[1,0]
	v_pk_mul_f32 v[36:37], v[36:37], v[0:1] op_sel_hi:[1,0]
	v_pk_mul_f32 v[34:35], v[34:35], v[0:1] op_sel_hi:[1,0]
	v_pk_mul_f32 v[32:33], v[32:33], v[0:1] op_sel_hi:[1,0]
	v_pk_mul_f32 v[30:31], v[30:31], v[0:1] op_sel_hi:[1,0]
	v_pk_mul_f32 v[28:29], v[28:29], v[0:1] op_sel_hi:[1,0]
	v_pk_mul_f32 v[26:27], v[26:27], v[0:1] op_sel_hi:[1,0]
	v_pk_mul_f32 v[24:25], v[24:25], v[0:1] op_sel_hi:[1,0]
	v_pk_mul_f32 v[22:23], v[22:23], v[0:1] op_sel_hi:[1,0]
	v_pk_mul_f32 v[20:21], v[20:21], v[0:1] op_sel_hi:[1,0]
	v_pk_mul_f32 v[18:19], v[18:19], v[0:1] op_sel_hi:[1,0]
	v_pk_mul_f32 v[16:17], v[16:17], v[0:1] op_sel_hi:[1,0]
.Lnsw1_keep0:
	v_sub_f32_e32 v80, v80, v168
	v_exp_f32_e32 v80, v80
	v_sub_f32_e32 v81, v81, v168
	v_exp_f32_e32 v81, v81
	v_sub_f32_e32 v82, v82, v168
	v_exp_f32_e32 v82, v82
	v_add_f32_e32 v213, v81, v80
	v_sub_f32_e32 v83, v83, v168
	v_exp_f32_e32 v83, v83
	v_add_f32_e32 v213, v82, v213
	v_cvt_pk_bf16_f32 v176, v80, v81
	v_sub_f32_e32 v84, v84, v168
	v_exp_f32_e32 v84, v84
	v_add_f32_e32 v213, v83, v213
	v_sub_f32_e32 v85, v85, v168
	v_exp_f32_e32 v85, v85
	v_add_f32_e32 v213, v84, v213
	v_cvt_pk_bf16_f32 v177, v82, v83
	v_sub_f32_e32 v86, v86, v168
	v_exp_f32_e32 v86, v86
	v_add_f32_e32 v213, v85, v213
	v_sub_f32_e32 v87, v87, v168
	v_exp_f32_e32 v87, v87
	v_add_f32_e32 v213, v86, v213
	v_cvt_pk_bf16_f32 v178, v84, v85
	v_sub_f32_e32 v88, v88, v168
	v_exp_f32_e32 v88, v88
	v_add_f32_e32 v213, v87, v213
	v_sub_f32_e32 v89, v89, v168
	v_exp_f32_e32 v89, v89
	v_add_f32_e32 v213, v88, v213
	v_cvt_pk_bf16_f32 v179, v86, v87
	v_sub_f32_e32 v90, v90, v168
	v_exp_f32_e32 v90, v90
	v_add_f32_e32 v213, v89, v213
	s_waitcnt lgkmcnt(7)
	v_mfma_f32_32x32x16_bf16 v[32:47], v[64:67], v[176:179], v[32:47]
	s_waitcnt lgkmcnt(6)
	v_mfma_f32_32x32x16_bf16 v[16:31], v[68:71], v[176:179], v[16:31]
	v_sub_f32_e32 v91, v91, v168
	v_exp_f32_e32 v91, v91
	v_add_f32_e32 v213, v90, v213
	v_cvt_pk_bf16_f32 v180, v88, v89
	v_sub_f32_e32 v92, v92, v168
	v_exp_f32_e32 v92, v92
	v_add_f32_e32 v213, v91, v213
	v_sub_f32_e32 v93, v93, v168
	v_exp_f32_e32 v93, v93
	v_add_f32_e32 v213, v92, v213
	v_cvt_pk_bf16_f32 v181, v90, v91
	v_sub_f32_e32 v94, v94, v168
	v_exp_f32_e32 v94, v94
	v_add_f32_e32 v213, v93, v213
	v_sub_f32_e32 v95, v95, v168
	v_exp_f32_e32 v95, v95
	v_add_f32_e32 v213, v94, v213
	v_cvt_pk_bf16_f32 v182, v92, v93
	v_add_f32_e32 v213, v95, v213
	v_cvt_pk_bf16_f32 v183, v94, v95
	v_add_f32_e32 v169, v169, v213
	s_nop 0
	s_waitcnt lgkmcnt(5)
	v_mfma_f32_32x32x16_bf16 v[32:47], v[72:75], v[180:183], v[32:47]
	s_waitcnt lgkmcnt(4)
	v_mfma_f32_32x32x16_bf16 v[16:31], v[76:79], v[180:183], v[16:31]
	v_cmp_gt_f32_e32 vcc, v175, v219
	s_cmp_eq_u64 vcc, 0
	s_cbranch_scc1 .Lnsw1_keep1
	s_nop 0
	ds_bpermute_b32 v214, v119, v175
	s_waitcnt lgkmcnt(0)
	v_max_f32_e32 v175, v175, v214
	v_max_f32_e32 v173, v168, v175
	v_sub_f32_e32 v0, v168, v173
	v_exp_f32_e32 v0, v0
	v_mov_b32_e32 v168, v173
	v_add_f32_e32 v219, 0x41200000, v173
	v_mul_f32_e32 v169, v169, v0
	v_pk_mul_f32 v[46:47], v[46:47], v[0:1] op_sel_hi:[1,0]
	v_pk_mul_f32 v[44:45], v[44:45], v[0:1] op_sel_hi:[1,0]
	v_pk_mul_f32 v[42:43], v[42:43], v[0:1] op_sel_hi:[1,0]
	v_pk_mul_f32 v[40:41], v[40:41], v[0:1] op_sel_hi:[1,0]
	v_pk_mul_f32 v[38:39], v[38:39], v[0:1] op_sel_hi:[1,0]
	v_pk_mul_f32 v[36:37], v[36:37], v[0:1] op_sel_hi:[1,0]
	v_pk_mul_f32 v[34:35], v[34:35], v[0:1] op_sel_hi:[1,0]
	v_pk_mul_f32 v[32:33], v[32:33], v[0:1] op_sel_hi:[1,0]
	v_pk_mul_f32 v[30:31], v[30:31], v[0:1] op_sel_hi:[1,0]
	v_pk_mul_f32 v[28:29], v[28:29], v[0:1] op_sel_hi:[1,0]
	v_pk_mul_f32 v[26:27], v[26:27], v[0:1] op_sel_hi:[1,0]
	v_pk_mul_f32 v[24:25], v[24:25], v[0:1] op_sel_hi:[1,0]
	v_pk_mul_f32 v[22:23], v[22:23], v[0:1] op_sel_hi:[1,0]
	v_pk_mul_f32 v[20:21], v[20:21], v[0:1] op_sel_hi:[1,0]
	v_pk_mul_f32 v[18:19], v[18:19], v[0:1] op_sel_hi:[1,0]
	v_pk_mul_f32 v[16:17], v[16:17], v[0:1] op_sel_hi:[1,0]
.Lnsw1_keep1:
	v_sub_f32_e32 v48, v48, v168
	v_exp_f32_e32 v48, v48
	v_sub_f32_e32 v49, v49, v168
	v_exp_f32_e32 v49, v49
	v_sub_f32_e32 v50, v50, v168
	v_exp_f32_e32 v50, v50
	v_add_f32_e32 v213, v49, v48
	v_sub_f32_e32 v51, v51, v168
	v_exp_f32_e32 v51, v51
	v_add_f32_e32 v213, v50, v213
	v_cvt_pk_bf16_f32 v80, v48, v49
	v_sub_f32_e32 v52, v52, v168
	v_exp_f32_e32 v52, v52
	v_add_f32_e32 v213, v51, v213
	v_sub_f32_e32 v53, v53, v168
	v_exp_f32_e32 v53, v53
	v_add_f32_e32 v213, v52, v213
	v_cvt_pk_bf16_f32 v81, v50, v51
	v_sub_f32_e32 v54, v54, v168
	v_exp_f32_e32 v54, v54
	v_add_f32_e32 v213, v53, v213
	v_sub_f32_e32 v55, v55, v168
	v_exp_f32_e32 v55, v55
	v_add_f32_e32 v213, v54, v213
	v_cvt_pk_bf16_f32 v82, v52, v53
	v_sub_f32_e32 v56, v56, v168
	v_exp_f32_e32 v56, v56
	v_add_f32_e32 v213, v55, v213
	v_sub_f32_e32 v57, v57, v168
	v_exp_f32_e32 v57, v57
	v_add_f32_e32 v213, v56, v213
	v_cvt_pk_bf16_f32 v83, v54, v55
	v_sub_f32_e32 v58, v58, v168
	v_exp_f32_e32 v58, v58
	v_add_f32_e32 v213, v57, v213
	s_waitcnt lgkmcnt(3)
	v_mfma_f32_32x32x16_bf16 v[32:47], v[220:223], v[80:83], v[32:47]
	s_waitcnt lgkmcnt(2)
	v_mfma_f32_32x32x16_bf16 v[16:31], v[224:227], v[80:83], v[16:31]
	v_sub_f32_e32 v59, v59, v168
	v_exp_f32_e32 v59, v59
	v_add_f32_e32 v213, v58, v213
	v_cvt_pk_bf16_f32 v84, v56, v57
	v_sub_f32_e32 v60, v60, v168
	v_exp_f32_e32 v60, v60
	v_add_f32_e32 v213, v59, v213
	v_sub_f32_e32 v61, v61, v168
	v_exp_f32_e32 v61, v61
	v_add_f32_e32 v213, v60, v213
	v_cvt_pk_bf16_f32 v85, v58, v59
	v_sub_f32_e32 v62, v62, v168
	v_exp_f32_e32 v62, v62
	v_add_f32_e32 v213, v61, v213
	v_sub_f32_e32 v63, v63, v168
	v_exp_f32_e32 v63, v63
	v_add_f32_e32 v213, v62, v213
	v_cvt_pk_bf16_f32 v86, v60, v61
	v_add_f32_e32 v213, v63, v213
	v_cvt_pk_bf16_f32 v87, v62, v63
	v_add_f32_e32 v169, v169, v213
	s_nop 0
	s_waitcnt lgkmcnt(1)
	v_mfma_f32_32x32x16_bf16 v[32:47], v[228:231], v[84:87], v[32:47]
	s_waitcnt lgkmcnt(0)
	v_mfma_f32_32x32x16_bf16 v[16:31], v[232:235], v[84:87], v[16:31]
	s_branch .LBB0_314
